# GLA scan: raw q/k prefetched straight into the transforming thread's registers (16 dword loads), no LDS staging of raw q/k (4 ds_write_b128 + 16 ds_read_b32 per thread-step removed)
# speedup vs baseline: 1.0034x; 1.0034x over previous
; __device__ __forceinline__ void scan_unit(const int unit, const Args& a, unsigned char* lds, const int mk_wid) {
;     ...
;     bf16x8 qraw[2], kraw[2], vraw[4]; bf16x8 lraw = bf16x8{};
;     ...
;     GLA_LOAD(0);
.LBB0_416:
	s_or_b64 exec, exec, s[22:23]
	s_mov_b32 s4, 0x2a00000
	s_and_b64 s[20:21], s[2:3], exec
	s_cselect_b32 s4, s4, 0x1aa00000
	s_add_u32 s4, s38, s4
	s_addc_u32 s9, s39, 0
	s_lshl_b64 s[20:21], s[18:19], 11
	s_lshl_b32 s18, s35, 1
	s_add_u32 s18, s4, s18
	s_addc_u32 s19, s9, 0
	s_lshr_b32 s4, s33, 8
	s_lshl_b32 s9, s4, 10
	s_add_i32 s44, s9, 0
	s_lshl_b32 s4, s4, 14
	s_add_i32 s9, 0, 0x16c00
	s_add_i32 s45, s9, s4
	s_lshl_b32 s22, s34, 2
	s_add_i32 s44, s44, 0x1ec00
	s_add_i32 s45, s45, s22
	s_lshl_b32 s22, s27, 1
	s_add_u32 s22, s38, s22
	s_addc_u32 s23, s39, 0
	s_add_u32 s22, s22, 0xd600000
	s_addc_u32 s23, s23, 0
	s_cmpk_lt_u32 s33, 0x100
	v_lshl_add_u64 v[152:153], v[0:1], 1, s[24:25]
	s_cselect_b64 s[24:25], -1, 0
	s_lshl_b32 s27, s70, 4
	s_and_b32 s46, s27, 0x3fffffe0
	s_lshl_b32 s27, s70, 5
	s_and_b32 s47, s27, 32
	s_cmp_lg_u32 0, -1
	s_cselect_b32 s27, 0, 0
	s_add_i32 s4, s27, s4
	s_lshl_b32 s26, s26, 9
	s_add_i32 s48, s4, s26
	v_mov_b32_e32 v155, 0
	s_waitcnt vmcnt(0)
	v_mov_b32_e32 v128, 0
	v_cvt_pk_bf16_f32 v108, v5, v7
	v_cvt_pk_bf16_f32 v109, v2, v8
	v_cvt_pk_bf16_f32 v110, v3, v4
	v_cvt_pk_bf16_f32 v111, v6, v9
	s_mov_b32 s34, -1
	s_add_i32 s48, s48, 0xc800
	s_add_i32 s49, s9, s72
	s_mov_b32 s50, 38
	s_movk_i32 s51, 0x110
	s_movk_i32 s52, 0x80
	s_add_i32 s53, 0, 0x1ec00
	s_mov_b32 s54, 0xbfb8aa3b
	s_add_i32 s55, 0, 0x1f400
	s_movk_i32 s56, 0x1100
	s_add_i32 s57, 0, 0x14800
	v_mov_b32_e32 v129, v128
	v_mov_b32_e32 v130, v128
	v_mov_b32_e32 v131, v128
	v_mov_b32_e32 v132, v128
	v_mov_b32_e32 v133, v128
	v_mov_b32_e32 v134, v128
	v_mov_b32_e32 v135, v128
	v_mov_b32_e32 v0, v155
	v_mov_b32_e32 v1, v155
	v_mov_b32_e32 v2, v155
	v_mov_b32_e32 v3, v155
	v_mov_b32_e32 v4, v155
	v_mov_b32_e32 v5, v155
	v_mov_b32_e32 v6, v155
	v_mov_b32_e32 v7, v155
	v_mov_b32_e32 v8, v155
	v_mov_b32_e32 v9, v155
	v_mov_b32_e32 v10, v155
	v_mov_b32_e32 v11, v155
	v_mov_b32_e32 v12, v155
	v_mov_b32_e32 v13, v155
	v_mov_b32_e32 v14, v155
	v_mov_b32_e32 v15, v155
	v_mov_b32_e32 v16, v155
	v_mov_b32_e32 v17, v155
	v_mov_b32_e32 v18, v155
	v_mov_b32_e32 v19, v155
	v_mov_b32_e32 v20, v155
	v_mov_b32_e32 v21, v155
	v_mov_b32_e32 v22, v155
	v_mov_b32_e32 v23, v155
	v_mov_b32_e32 v24, v155
	v_mov_b32_e32 v25, v155
	v_mov_b32_e32 v26, v155
	v_mov_b32_e32 v27, v155
	v_mov_b32_e32 v28, v155
	v_mov_b32_e32 v29, v155
	v_mov_b32_e32 v30, v155
	v_mov_b32_e32 v31, v155
	v_mov_b32_e32 v32, v155
	v_mov_b32_e32 v33, v155
	v_mov_b32_e32 v34, v155
	v_mov_b32_e32 v35, v155
	v_mov_b32_e32 v36, v155
	v_mov_b32_e32 v37, v155
	v_mov_b32_e32 v38, v155
	v_mov_b32_e32 v39, v155
	v_mov_b32_e32 v40, v155
	v_mov_b32_e32 v41, v155
	v_mov_b32_e32 v42, v155
	v_mov_b32_e32 v43, v155
	v_mov_b32_e32 v44, v155
	v_mov_b32_e32 v45, v155
	v_mov_b32_e32 v46, v155
	v_mov_b32_e32 v47, v155
	v_mov_b32_e32 v48, v155
	v_mov_b32_e32 v49, v155
	v_mov_b32_e32 v50, v155
	v_mov_b32_e32 v51, v155
	v_mov_b32_e32 v52, v155
	v_mov_b32_e32 v53, v155
	v_mov_b32_e32 v54, v155
	v_mov_b32_e32 v55, v155
	v_mov_b32_e32 v56, v155
	v_mov_b32_e32 v57, v155
	v_mov_b32_e32 v58, v155
	v_mov_b32_e32 v59, v155
	v_mov_b32_e32 v60, v155
	v_mov_b32_e32 v61, v155
	v_mov_b32_e32 v62, v155
	v_mov_b32_e32 v63, v155
	v_mbcnt_lo_u32_b32 v64, -1, 0
	v_mbcnt_hi_u32_b32 v64, -1, v64
	v_add_u32_e32 v64, s72, v64
	v_lshrrev_b32_e32 v65, 4, v64
	v_and_b32_e32 v67, 15, v64
	v_lshlrev_b32_e32 v67, 4, v67
	v_sub_u32_e32 v66, 63, v65
	v_cndmask_b32_e64 v66, v66, v65, s[2:3]
	v_add_u32_e32 v66, s12, v66
	v_lshl_add_u32 v245, v66, 10, v67
	v_add_u32_e32 v68, 32, v65
	v_sub_u32_e32 v69, 31, v65
	v_cndmask_b32_e64 v68, v69, v68, s[2:3]
	v_add_u32_e32 v68, s12, v68
	v_lshl_add_u32 v246, v68, 10, v67
	v_lshrrev_b32_e32 v65, 5, v64
	v_and_b32_e32 v67, 31, v64
	v_lshlrev_b32_e32 v67, 4, v67
	v_lshrrev_b32_e32 v65, 1, v64
	v_sub_u32_e32 v69, 63, v65
	v_cndmask_b32_e64 v68, v69, v65, s[2:3]
	v_add_u32_e32 v68, s12, v68
	v_and_b32_e32 v67, 1, v64
	v_lshlrev_b32_e32 v67, 4, v67
	v_lshl_add_u32 v251, v68, 6, v67
	v_mbcnt_lo_u32_b32 v66, -1, 0
	v_mbcnt_hi_u32_b32 v66, -1, v66
	s_lshl_b32 s96, s70, 3
	s_sub_i32 s97, 56, s96
	s_bitcmp1_b32 s8, 0
	s_cselect_b32 s96, s97, s96
	s_add_i32 s96, s96, s12
	s_lshl_b32 s96, s96, 10
	v_lshl_add_u32 v245, v66, 2, s96
	s_bitcmp1_b32 s8, 0
	s_cselect_b32 s97, 3, 0
	s_lshl_b32 s97, s97, 16
	v_add_u32_e32 v64, s97, v245
	v_add_u32_e32 v65, 0x1000, v64
	s_bitcmp1_b32 s8, 0
	s_cbranch_scc1 .Lscan_qk_rev2
	global_load_dword v100, v64, s[14:15]
	global_load_dword v101, v64, s[14:15] offset:1024
	global_load_dword v102, v64, s[14:15] offset:2048
	global_load_dword v103, v64, s[14:15] offset:3072
	global_load_dword v104, v65, s[14:15]
	global_load_dword v105, v65, s[14:15] offset:1024
	global_load_dword v106, v65, s[14:15] offset:2048
	global_load_dword v107, v65, s[14:15] offset:3072
	s_branch .Lscan_qk_done2
.Lscan_qk_rev2:
	global_load_dword v100, v65, s[14:15] offset:3072
	global_load_dword v101, v65, s[14:15] offset:2048
	global_load_dword v102, v65, s[14:15] offset:1024
	global_load_dword v103, v65, s[14:15]
	global_load_dword v104, v64, s[14:15] offset:3072
	global_load_dword v105, v64, s[14:15] offset:2048
	global_load_dword v106, v64, s[14:15] offset:1024
	global_load_dword v107, v64, s[14:15]
.Lscan_qk_done2:
	v_mov_b32_e32 v128, 0
	v_mov_b32_e32 v129, 0
	v_mov_b32_e32 v130, 0
	v_mov_b32_e32 v131, 0
	v_mov_b32_e32 v132, 0
	v_mov_b32_e32 v133, 0
	v_mov_b32_e32 v134, 0
	v_mov_b32_e32 v135, 0
	v_mbcnt_lo_u32_b32 v66, -1, 0
	v_mbcnt_hi_u32_b32 v66, -1, v66
	v_bfe_u32 v67, v66, 4, 1
	v_lshlrev_b32_e32 v67, 3, v67
	v_bfe_u32 v68, v66, 2, 2
	v_add_u32_e32 v67, v67, v68
	s_and_b32 s96, s70, 3
	s_lshl_b32 s96, s96, 4
	v_add_u32_e32 v67, s96, v67
	v_lshrrev_b32_e32 v68, 5, v66
	v_lshlrev_b32_e32 v68, 6, v68
	v_and_b32_e32 v69, 3, v66
	v_lshl_add_u32 v68, v69, 4, v68
	s_lshr_b32 s96, s70, 2
	s_lshl_b32 s96, s96, 8
	v_add_u32_e32 v68, s96, v68
	v_sub_u32_e32 v69, 63, v67
	v_cndmask_b32_e64 v69, v69, v67, s[2:3]
	v_add_u32_e32 v69, s12, v69
	v_lshl_add_u32 v247, v69, 11, v68
	v_add_u32_e32 v248, 0x80, v247
	v_add_u32_e32 v67, 4, v67
	v_sub_u32_e32 v69, 63, v67
	v_cndmask_b32_e64 v69, v69, v67, s[2:3]
	v_add_u32_e32 v69, s12, v69
	v_lshl_add_u32 v249, v69, 11, v68
	v_add_u32_e32 v250, 0x80, v249

; __device__ __forceinline__ int v_st(int k, int c) { const int kk = (k & ~0xC) | ((k & 4) << 1) | ((k & 8) >> 1); return ((kk >> 3) * 4 + (c >> 5)) * 512 + ((kk & 7) * 32 + (c & 31)) * 2; }
; #define OPAQUE_TID(name) int name = MK_TID; asm volatile("" : "+v"(name))
; __device__ __forceinline__ void scan_unit(const int unit, const Args& a, unsigned char* lds, const int mk_wid) {
;     ...
;         { OPAQUE_TID(t_);
; #pragma unroll
;           for (int p = 0; p < 2; ++p) { const int i_ = p * 32 + (t_ >> 4), c_ = (t_ & 15) * 8; *(bf16x8*)(qe + i_ * QP + c_) = qraw[p]; *(bf16x8*)(ke + i_ * QP + c_) = kraw[p]; }
; #pragma unroll
;           for (int p = 0; p < 4; ++p) { const int i_ = p * 16 + (t_ >> 5), c8 = t_ & 31; *(bf16x8*)(lds + L_V + (c8 >> 4) * 16384 + v_st(i_, (c8 & 15) * 8)) = vraw[p]; }
;           if (t_ < 128) *(bf16x8*)(lds + L_LR + (t_ >> 1) * 32 + (t_ & 1) * 16) = lraw; }
.Lscan_cc_done:
	s_lshl_b32 s96, s96, 17
	s_lshl_b32 s97, s70, 12
	s_add_i32 s97, s97, 0xc800
	s_waitcnt vmcnt(0)
	s_cmp_lt_u32 s70, 2
	s_cbranch_scc0 .Lscan_nolrw
	v_lshrrev_b32_e32 v66, 1, v64
	v_lshlrev_b32_e32 v66, 5, v66
	v_and_b32_e32 v67, 1, v64
	v_lshl_add_u32 v66, v67, 4, v66
	v_add_u32_e32 v66, s53, v66
	ds_write_b128 v66, v[96:99]

; __device__ __forceinline__ int crow(int r, int hi) { return (r & 3) + 8 * (r >> 2) + 4 * hi; }
; #define OPAQUE_TID(name) int name = MK_TID; asm volatile("" : "+v"(name))
; __device__ __forceinline__ void scan_unit(const int unit, const Args& a, unsigned char* lds, const int mk_wid) {
;     ...
;         { OPAQUE_TID(t_); const int lane = t_ & 63, r32 = lane & 31, hi = lane >> 5; const int tt = wid >> 2, ct = wid & 3;
;           const bf16x8 af = *(const bf16x8*)(lds + L_LR + (tt * 32 + r32) * 32 + hi * 16);
;           const f32x16 z = __builtin_amdgcn_mfma_f32_32x32x16_bf16(af, upf, f32x16{}, 0, 0, 0);
;           float* lw = las + (tt * 32 + 4 * hi) * 128 + ct * 32 + r32;
; #pragma unroll
;           for (int r = 0; r < 16; ++r) { const float zz = z[r] + biasc;
;               lw[crow(r, 0) * 128] = (fminf(zz, 0.f) - __builtin_amdgcn_logf(1.f + __builtin_amdgcn_exp2f(-1.4426950408889634f * fabsf(zz))) * 0.6931471805599453f) * (1.f / 16.f); } }
;         __syncthreads();
.Lscan_noflush:
	s_waitcnt lgkmcnt(0)
	s_barrier
	v_mbcnt_lo_u32_b32 v64, -1, 0
	v_mbcnt_hi_u32_b32 v64, -1, v64
	s_nop 0
	v_add_u32_e32 v64, s72, v64
	s_nop 0
	v_and_b32_e32 v68, 31, v64
	v_bfe_u32 v69, v64, 5, 1
	v_lshlrev_b32_e32 v64, 5, v68
	v_lshlrev_b32_e32 v65, 4, v69
	v_add3_u32 v64, s44, v64, v65
	ds_read_b128 v[64:67], v64
	v_lshlrev_b32_e32 v69, 11, v69
	v_lshlrev_b32_e32 v68, 2, v68
	v_add3_u32 v80, s45, v69, v68
	s_waitcnt lgkmcnt(0)
	v_mfma_f32_32x32x16_bf16 v[64:79], v[64:67], v[108:111], 0
	s_nop 11
	v_add_f32_e32 v64, v156, v64
	v_add_f32_e32 v65, v156, v65
	v_mul_f32_e64 v81, |v64|, s54
	v_mul_f32_e64 v82, |v65|, s54
	v_exp_f32_e32 v81, v81
	v_exp_f32_e32 v82, v82
	v_add_f32_e32 v66, v156, v66
	v_min_f32_e32 v64, 0, v64
	v_add_f32_e32 v81, 1.0, v81
	v_add_f32_e32 v82, 1.0, v82
	v_log_f32_e32 v81, v81
	v_log_f32_e32 v82, v82
	v_min_f32_e32 v65, 0, v65
	v_mul_f32_e64 v83, |v66|, s54
	v_fmac_f32_e32 v64, 0xbf317218, v81
	v_fmac_f32_e32 v65, 0xbf317218, v82
	v_add_f32_e32 v67, v156, v67
	v_exp_f32_e32 v83, v83
	v_mul_f32_e32 v64, 0x3db8aa3b, v64
	v_mul_f32_e32 v65, 0x3db8aa3b, v65
	ds_write2st64_b32 v80, v64, v65 offset1:2
	v_mul_f32_e64 v64, |v67|, s54
	v_exp_f32_e32 v64, v64
	v_add_f32_e32 v65, 1.0, v83
	v_log_f32_e32 v65, v65
	v_min_f32_e32 v66, 0, v66
	v_add_f32_e32 v64, 1.0, v64
	v_log_f32_e32 v64, v64
	v_fmac_f32_e32 v66, 0xbf317218, v65
	v_mul_f32_e32 v65, 0x3db8aa3b, v66
	v_min_f32_e32 v66, 0, v67
	v_fmac_f32_e32 v66, 0xbf317218, v64
	v_mul_f32_e32 v64, 0x3db8aa3b, v66
	ds_write2st64_b32 v80, v65, v64 offset0:4 offset1:6
	v_add_f32_e32 v64, v156, v68
	v_mul_f32_e64 v65, |v64|, s54
	v_add_f32_e32 v66, v156, v69
	v_exp_f32_e32 v65, v65
	v_mul_f32_e64 v67, |v66|, s54
	v_exp_f32_e32 v67, v67
	v_min_f32_e32 v64, 0, v64
	v_add_f32_e32 v65, 1.0, v65
	v_log_f32_e32 v65, v65
	v_add_f32_e32 v67, 1.0, v67
	v_log_f32_e32 v67, v67
	v_fmac_f32_e32 v64, 0xbf317218, v65
	v_min_f32_e32 v65, 0, v66
	v_fmac_f32_e32 v65, 0xbf317218, v67
	v_mul_f32_e32 v64, 0x3db8aa3b, v64
	v_mul_f32_e32 v65, 0x3db8aa3b, v65
	ds_write2st64_b32 v80, v64, v65 offset0:16 offset1:18
	v_add_f32_e32 v64, v156, v70
	v_mul_f32_e64 v65, |v64|, s54
	v_add_f32_e32 v66, v156, v71
	v_exp_f32_e32 v65, v65
	v_mul_f32_e64 v67, |v66|, s54
	v_exp_f32_e32 v67, v67
	v_min_f32_e32 v64, 0, v64
	v_add_f32_e32 v65, 1.0, v65
	v_log_f32_e32 v65, v65
	v_add_f32_e32 v67, 1.0, v67
	v_log_f32_e32 v67, v67
	v_fmac_f32_e32 v64, 0xbf317218, v65
	v_min_f32_e32 v65, 0, v66
	v_fmac_f32_e32 v65, 0xbf317218, v67
	v_mul_f32_e32 v64, 0x3db8aa3b, v64
	v_mul_f32_e32 v65, 0x3db8aa3b, v65
	ds_write2st64_b32 v80, v64, v65 offset0:20 offset1:22
	v_add_f32_e32 v64, v156, v72
	v_mul_f32_e64 v65, |v64|, s54
	v_add_f32_e32 v66, v156, v73
	v_exp_f32_e32 v65, v65
	v_mul_f32_e64 v67, |v66|, s54
	v_exp_f32_e32 v67, v67
	v_min_f32_e32 v64, 0, v64
	v_add_f32_e32 v65, 1.0, v65
	v_log_f32_e32 v65, v65
	v_add_f32_e32 v67, 1.0, v67
	v_log_f32_e32 v67, v67
	v_fmac_f32_e32 v64, 0xbf317218, v65
	v_min_f32_e32 v65, 0, v66
	v_fmac_f32_e32 v65, 0xbf317218, v67
	v_mul_f32_e32 v64, 0x3db8aa3b, v64
	v_mul_f32_e32 v65, 0x3db8aa3b, v65
	ds_write2st64_b32 v80, v64, v65 offset0:32 offset1:34
	v_add_f32_e32 v64, v156, v74
	v_mul_f32_e64 v65, |v64|, s54
	v_add_f32_e32 v66, v156, v75
	v_exp_f32_e32 v65, v65
	v_mul_f32_e64 v67, |v66|, s54
	v_exp_f32_e32 v67, v67
	v_min_f32_e32 v64, 0, v64
	v_add_f32_e32 v65, 1.0, v65
	v_log_f32_e32 v65, v65
	v_add_f32_e32 v67, 1.0, v67
	v_log_f32_e32 v67, v67
	v_fmac_f32_e32 v64, 0xbf317218, v65
	v_min_f32_e32 v65, 0, v66
	v_fmac_f32_e32 v65, 0xbf317218, v67
	v_mul_f32_e32 v64, 0x3db8aa3b, v64
	v_mul_f32_e32 v65, 0x3db8aa3b, v65
	ds_write2st64_b32 v80, v64, v65 offset0:36 offset1:38
	v_add_f32_e32 v64, v156, v76
	v_mul_f32_e64 v65, |v64|, s54
	v_add_f32_e32 v66, v156, v77
	v_exp_f32_e32 v65, v65
	v_mul_f32_e64 v67, |v66|, s54
	v_exp_f32_e32 v67, v67
	v_min_f32_e32 v64, 0, v64
	v_add_f32_e32 v65, 1.0, v65
	v_log_f32_e32 v65, v65
	v_add_f32_e32 v67, 1.0, v67
	v_log_f32_e32 v67, v67
	v_fmac_f32_e32 v64, 0xbf317218, v65
	v_min_f32_e32 v65, 0, v66
	v_fmac_f32_e32 v65, 0xbf317218, v67
	v_mul_f32_e32 v64, 0x3db8aa3b, v64
	v_mul_f32_e32 v65, 0x3db8aa3b, v65
	ds_write2st64_b32 v80, v64, v65 offset0:48 offset1:50
	v_add_f32_e32 v64, v156, v78
	v_mul_f32_e64 v65, |v64|, s54
	v_add_f32_e32 v66, v156, v79
	v_exp_f32_e32 v65, v65
	v_mul_f32_e64 v67, |v66|, s54
	v_exp_f32_e32 v67, v67
	v_min_f32_e32 v64, 0, v64
	v_add_f32_e32 v65, 1.0, v65
	v_log_f32_e32 v65, v65
	v_add_f32_e32 v67, 1.0, v67
	v_log_f32_e32 v67, v67
	v_fmac_f32_e32 v64, 0xbf317218, v65
	v_min_f32_e32 v65, 0, v66
	v_fmac_f32_e32 v65, 0xbf317218, v67
	v_mul_f32_e32 v64, 0x3db8aa3b, v64
	v_mul_f32_e32 v65, 0x3db8aa3b, v65
	ds_write2st64_b32 v80, v64, v65 offset0:52 offset1:54
	s_waitcnt lgkmcnt(0)
	s_barrier
; __device__ __forceinline__ int v_st(int k, int c) { const int kk = (k & ~0xC) | ((k & 4) << 1) | ((k & 8) >> 1); return ((kk >> 3) * 4 + (c >> 5)) * 512 + ((kk & 7) * 32 + (c & 31)) * 2; }
; __device__ __forceinline__ float bf2f(short s) { return __uint_as_float(((unsigned)(unsigned short)s) << 16); }
; __device__ __forceinline__ float bf2f(u16 u) { return __uint_as_float((unsigned)u << 16); }
; #define OPAQUE_TID(name) int name = MK_TID; asm volatile("" : "+v"(name))
; __device__ __forceinline__ void scan_unit(const int unit, const Args& a, unsigned char* lds, const int mk_wid) {
;     ...
;         { OPAQUE_TID(t_); const int c = t_ & 127, g = t_ >> 7;
;           float bl[16]; float run = 0.f;
;           { const float* lp = las + (g * 16) * 128 + c;
; #pragma unroll
;             for (int ii = 0; ii < 16; ++ii) { run += lp[ii * 128]; bl[ii] = run; } }
;           gs[g * 128 + c] = run;
;           __syncthreads();
;           const float g0 = gs[c], g1 = gs[128 + c], g2 = gs[256 + c], g3 = gs[384 + c];
;           const float off = (g > 0 ? g0 : 0.f) + (g > 1 ? g1 : 0.f) + (g > 2 ? g2 : 0.f);
;           const float btot = (g0 + g1) + (g2 + g3);
;           const float dlc = __builtin_amdgcn_exp2f(btot * 1.4426950408889634f);
;           if (g == 0) dl[c] = dlc;
;           u16* qcol = qe + (g * 16) * QP + c; u16* kcol = ke + (g * 16) * QP + c; unsigned char* kdb = lds + L_KD + v_st(g * 16, c);
; #pragma unroll
;           for (int ii = 0; ii < 16; ++ii) { const float bb = bl[ii] + off;
;               const float qf = bf2f(qcol[ii * QP]), kf = bf2f(kcol[ii * QP]);
;               const float e = __builtin_amdgcn_exp2f(bb * 1.4426950408889634f), ker = kf * __builtin_amdgcn_rcpf(e);
	v_mbcnt_lo_u32_b32 v64, -1, 0
	v_mbcnt_hi_u32_b32 v64, -1, v64
	s_lshl_b32 s96, s70, 12
	s_add_i32 s96, s96, s9
	v_lshl_add_u32 v65, v64, 3, s96
	ds_read_b64 v[170:171], v65
	ds_read_b64 v[172:173], v65 offset:512
	ds_read_b64 v[174:175], v65 offset:1024
	ds_read_b64 v[176:177], v65 offset:1536
	ds_read_b64 v[178:179], v65 offset:2048
	ds_read_b64 v[180:181], v65 offset:2560
	ds_read_b64 v[182:183], v65 offset:3072
	ds_read_b64 v[184:185], v65 offset:3584
	s_cmp_gt_u32 s70, 0
	s_cselect_b32 s97, 1.0, 0
	v_mov_b32_e32 v238, s97
	s_cmp_gt_u32 s70, 1
	s_cselect_b32 s97, 1.0, 0
	v_mov_b32_e32 v239, s97
	s_cmp_gt_u32 s70, 2
	s_cselect_b32 s97, 1.0, 0
	v_mov_b32_e32 v240, s97
	s_cmp_gt_u32 s70, 3
	s_cselect_b32 s97, 1.0, 0
	v_mov_b32_e32 v241, s97
	s_cmp_gt_u32 s70, 4
	s_cselect_b32 s97, 1.0, 0
	v_mov_b32_e32 v242, s97
	s_cmp_gt_u32 s70, 5
	s_cselect_b32 s97, 1.0, 0
	v_mov_b32_e32 v243, s97
	s_cmp_gt_u32 s70, 6
	s_cselect_b32 s97, 1.0, 0
	v_mov_b32_e32 v244, s97
	s_lshl_b32 s98, s70, 9
	s_add_i32 s98, s98, 0x20000
	v_lshl_add_u32 v66, v64, 3, s98
	v_lshlrev_b32_e32 v67, 3, v64
	v_add_u32_e32 v67, 0x20000, v67
	s_mul_i32 s99, s70, 0x880
	v_lshl_add_u32 v68, v64, 2, s99
	v_and_b32_e32 v94, 2, v64
	v_lshlrev_b32_e32 v94, 1, v94
	v_and_b32_e32 v95, 4, v64
	v_lshrrev_b32_e32 v95, 1, v95
	v_and_b32_e32 v70, 0xfffffff9, v64
	v_or3_b32 v94, v94, v95, v70
	v_lshl_add_u32 v94, v94, 2, s99
	s_lshr_b32 s98, s70, 1
	s_lshl_b32 s98, s98, 12
	s_and_b32 s99, s70, 1
	s_lshl_b32 s99, s99, 8
	s_add_i32 s98, s98, s99
	v_lshrrev_b32_e32 v69, 4, v64
	v_lshlrev_b32_e32 v69, 9, v69
	v_and_b32_e32 v70, 15, v64
	v_lshl_add_u32 v69, v70, 2, v69
	v_add_u32_e32 v69, s98, v69
	s_waitcnt lgkmcnt(7)
	v_add_f32_e32 v170, 0, v170
	v_add_f32_e32 v171, 0, v171
	s_waitcnt lgkmcnt(6)
	v_add_f32_e32 v172, v170, v172
	v_add_f32_e32 v173, v171, v173
	s_waitcnt lgkmcnt(5)
	v_add_f32_e32 v174, v172, v174
	v_add_f32_e32 v175, v173, v175
	s_waitcnt lgkmcnt(4)
	v_add_f32_e32 v176, v174, v176
	v_add_f32_e32 v177, v175, v177
	s_waitcnt lgkmcnt(3)
	v_add_f32_e32 v178, v176, v178
	v_add_f32_e32 v179, v177, v179
	s_waitcnt lgkmcnt(2)
	v_add_f32_e32 v180, v178, v180
	v_add_f32_e32 v181, v179, v181
	s_waitcnt lgkmcnt(1)
	v_add_f32_e32 v182, v180, v182
	v_add_f32_e32 v183, v181, v183
	s_waitcnt lgkmcnt(0)
	v_add_f32_e32 v184, v182, v184
	v_add_f32_e32 v185, v183, v185
	ds_write_b64 v66, v[184:185]
	s_waitcnt lgkmcnt(0)
	s_barrier
	ds_read_b64 v[72:73], v67
	ds_read_b64 v[74:75], v67 offset:512
	ds_read_b64 v[76:77], v67 offset:1024
	ds_read_b64 v[78:79], v67 offset:1536
	ds_read_b64 v[80:81], v67 offset:2048
	ds_read_b64 v[82:83], v67 offset:2560
	ds_read_b64 v[84:85], v67 offset:3072
	ds_read_b64 v[86:87], v67 offset:3584
	s_waitcnt lgkmcnt(0)
	v_mul_f32_e32 v88, v238, v72
	v_mul_f32_e32 v89, v238, v73
	v_fmac_f32_e32 v88, v239, v74
	v_fmac_f32_e32 v89, v239, v75
	v_fmac_f32_e32 v88, v240, v76
	v_fmac_f32_e32 v89, v240, v77
	v_fmac_f32_e32 v88, v241, v78
	v_fmac_f32_e32 v89, v241, v79
	v_fmac_f32_e32 v88, v242, v80
	v_fmac_f32_e32 v89, v242, v81
	v_fmac_f32_e32 v88, v243, v82
	v_fmac_f32_e32 v89, v243, v83
	v_fmac_f32_e32 v88, v244, v84
	v_fmac_f32_e32 v89, v244, v85
	v_add_f32_e32 v90, v72, v74
	v_add_f32_e32 v91, v73, v75
	v_add_f32_e32 v90, v90, v76
	v_add_f32_e32 v91, v91, v77
	v_add_f32_e32 v90, v90, v78
	v_add_f32_e32 v91, v91, v79
	v_add_f32_e32 v90, v90, v80
	v_add_f32_e32 v91, v91, v81
	v_add_f32_e32 v90, v90, v82
	v_add_f32_e32 v91, v91, v83
	v_add_f32_e32 v90, v90, v84
	v_add_f32_e32 v91, v91, v85
	v_add_f32_e32 v90, v90, v86
	v_add_f32_e32 v91, v91, v87
	v_mov_b32_e32 v92, v90
	v_mov_b32_e32 v93, v91
	v_exp_f32_e32 v92, v92
	v_exp_f32_e32 v93, v93
	v_add_f32_e32 v170, v170, v88
	v_add_f32_e32 v171, v171, v89
	v_add_f32_e32 v172, v172, v88
	v_add_f32_e32 v173, v173, v89
	v_add_f32_e32 v174, v174, v88
	v_add_f32_e32 v175, v175, v89
	v_add_f32_e32 v176, v176, v88
	v_add_f32_e32 v177, v177, v89
	v_add_f32_e32 v178, v178, v88
	v_add_f32_e32 v179, v179, v89
	v_add_f32_e32 v180, v180, v88
	v_add_f32_e32 v181, v181, v89
	v_add_f32_e32 v182, v182, v88
	v_add_f32_e32 v183, v183, v89
	v_add_f32_e32 v184, v184, v88
	v_add_f32_e32 v185, v185, v89
	v_exp_f32_e32 v170, v170
	v_exp_f32_e32 v171, v171
	v_exp_f32_e32 v172, v172
	v_exp_f32_e32 v173, v173
	v_exp_f32_e32 v174, v174
	v_exp_f32_e32 v175, v175
	v_exp_f32_e32 v176, v176
	v_exp_f32_e32 v177, v177
	v_exp_f32_e32 v178, v178
	v_exp_f32_e32 v179, v179
	v_exp_f32_e32 v180, v180
	v_exp_f32_e32 v181, v181
	v_exp_f32_e32 v182, v182
	v_exp_f32_e32 v183, v183
	v_exp_f32_e32 v184, v184
	v_exp_f32_e32 v185, v185
	v_rcp_f32_e32 v186, v170
	v_rcp_f32_e32 v187, v171
	v_rcp_f32_e32 v188, v172
	v_rcp_f32_e32 v189, v173
	v_rcp_f32_e32 v190, v174
	v_rcp_f32_e32 v191, v175
	v_rcp_f32_e32 v192, v176
	v_rcp_f32_e32 v193, v177
	v_rcp_f32_e32 v194, v178
	v_rcp_f32_e32 v195, v179
	v_rcp_f32_e32 v196, v180
	v_rcp_f32_e32 v197, v181
	v_rcp_f32_e32 v198, v182
	v_rcp_f32_e32 v199, v183
	v_rcp_f32_e32 v200, v184
	v_rcp_f32_e32 v201, v185
	v_mul_f32_e32 v170, 0x3db504f3, v170
	v_mul_f32_e32 v171, 0x3db504f3, v171
	v_mul_f32_e32 v172, 0x3db504f3, v172
	v_mul_f32_e32 v173, 0x3db504f3, v173
	v_mul_f32_e32 v174, 0x3db504f3, v174
	v_mul_f32_e32 v175, 0x3db504f3, v175
	v_mul_f32_e32 v176, 0x3db504f3, v176
	v_mul_f32_e32 v177, 0x3db504f3, v177
	v_mul_f32_e32 v178, 0x3db504f3, v178
	v_mul_f32_e32 v179, 0x3db504f3, v179
	v_mul_f32_e32 v180, 0x3db504f3, v180
	v_mul_f32_e32 v181, 0x3db504f3, v181
	v_mul_f32_e32 v182, 0x3db504f3, v182
	v_mul_f32_e32 v183, 0x3db504f3, v183
	v_mul_f32_e32 v184, 0x3db504f3, v184
	v_mul_f32_e32 v185, 0x3db504f3, v185
	s_cmp_lg_u32 s70, 0
	s_cbranch_scc1 .Lscan_c2_nodl
	v_lshlrev_b32_e32 v70, 3, v64
	v_add_u32_e32 v70, 0x1fc00, v70
	ds_write_b64 v70, v[92:93]
; __device__ __forceinline__ int v_st(int k, int c) { const int kk = (k & ~0xC) | ((k & 4) << 1) | ((k & 8) >> 1); return ((kk >> 3) * 4 + (c >> 5)) * 512 + ((kk & 7) * 32 + (c & 31)) * 2; }
; __device__ __forceinline__ float bf2f(short s) { return __uint_as_float(((unsigned)(unsigned short)s) << 16); }
; __device__ __forceinline__ float bf2f(u16 u) { return __uint_as_float((unsigned)u << 16); }
; __device__ __forceinline__ u16 f2bf(float f) { return (u16)(pk2(f, 0.f) & 0xffffu); }
; __device__ __forceinline__ void scan_unit(const int unit, const Args& a, unsigned char* lds, const int mk_wid) {
;     ...
;           u16* qcol = qe + (g * 16) * QP + c; u16* kcol = ke + (g * 16) * QP + c; unsigned char* kdb = lds + L_KD + v_st(g * 16, c);
; #pragma unroll
;           for (int ii = 0; ii < 16; ++ii) { const float bb = bl[ii] + off;
;               const float qf = bf2f(qcol[ii * QP]), kf = bf2f(kcol[ii * QP]);
;               const float e = __builtin_amdgcn_exp2f(bb * 1.4426950408889634f), ker = kf * __builtin_amdgcn_rcpf(e);
;               qcol[ii * QP] = f2bf(qf * (0.088388347648318440f * e));
;               kcol[ii * QP] = f2bf(ker);
;               *(u16*)(kdb + v_st(ii, 0)) = f2bf(ker * dlc); } }
.Lscan_c2_nodl:
	v_mov_b32_e32 v71, 0xffff0000
	v_lshlrev_b32_e32 v218, 16, v128
	v_and_b32_e32 v219, v71, v128
	v_lshlrev_b32_e32 v220, 16, v100
	v_and_b32_e32 v221, v71, v100
	v_mul_f32_e32 v218, v170, v218
	v_mul_f32_e32 v219, v171, v219
	v_mul_f32_e32 v220, v186, v220
	v_mul_f32_e32 v221, v187, v221
	v_cvt_pk_bf16_f32 v224, v218, v219
	v_mul_f32_e32 v222, v92, v220
	v_mul_f32_e32 v223, v93, v221
	v_cvt_pk_bf16_f32 v225, v220, v221
	ds_write_b32 v94, v224
	ds_write_b32 v94, v225 offset:17408
	v_cvt_pk_bf16_f32 v226, v222, v223
	ds_write_b32 v69, v226 offset:34816
	v_lshlrev_b32_e32 v228, 16, v129
	v_and_b32_e32 v229, v71, v129
	v_lshlrev_b32_e32 v230, 16, v101
	v_and_b32_e32 v231, v71, v101
	v_mul_f32_e32 v228, v172, v228
	v_mul_f32_e32 v229, v173, v229
	v_mul_f32_e32 v230, v188, v230
	v_mul_f32_e32 v231, v189, v231
	v_cvt_pk_bf16_f32 v234, v228, v229
	v_mul_f32_e32 v232, v92, v230
	v_mul_f32_e32 v233, v93, v231
	v_cvt_pk_bf16_f32 v235, v230, v231
	ds_write_b32 v94, v234 offset:272
	ds_write_b32 v94, v235 offset:17680
	v_cvt_pk_bf16_f32 v236, v232, v233
	ds_write_b32 v69, v236 offset:34880
	v_lshlrev_b32_e32 v218, 16, v130
	v_and_b32_e32 v219, v71, v130
	v_lshlrev_b32_e32 v220, 16, v102
	v_and_b32_e32 v221, v71, v102
	v_mul_f32_e32 v218, v174, v218
	v_mul_f32_e32 v219, v175, v219
	v_mul_f32_e32 v220, v190, v220
	v_mul_f32_e32 v221, v191, v221
	v_cvt_pk_bf16_f32 v224, v218, v219
	v_mul_f32_e32 v222, v92, v220
	v_mul_f32_e32 v223, v93, v221
	v_cvt_pk_bf16_f32 v225, v220, v221
	ds_write_b32 v94, v224 offset:544
	ds_write_b32 v94, v225 offset:17952
	v_cvt_pk_bf16_f32 v226, v222, v223
	ds_write_b32 v69, v226 offset:34944
	v_lshlrev_b32_e32 v228, 16, v131
	v_and_b32_e32 v229, v71, v131
	v_lshlrev_b32_e32 v230, 16, v103
	v_and_b32_e32 v231, v71, v103
	v_mul_f32_e32 v228, v176, v228
	v_mul_f32_e32 v229, v177, v229
	v_mul_f32_e32 v230, v192, v230
	v_mul_f32_e32 v231, v193, v231
	v_cvt_pk_bf16_f32 v234, v228, v229
	v_mul_f32_e32 v232, v92, v230
	v_mul_f32_e32 v233, v93, v231
	v_cvt_pk_bf16_f32 v235, v230, v231
	ds_write_b32 v94, v234 offset:816
	ds_write_b32 v94, v235 offset:18224
	v_cvt_pk_bf16_f32 v236, v232, v233
	ds_write_b32 v69, v236 offset:35008
	v_lshlrev_b32_e32 v218, 16, v132
	v_and_b32_e32 v219, v71, v132
	v_lshlrev_b32_e32 v220, 16, v104
	v_and_b32_e32 v221, v71, v104
	v_mul_f32_e32 v218, v178, v218
	v_mul_f32_e32 v219, v179, v219
	v_mul_f32_e32 v220, v194, v220
	v_mul_f32_e32 v221, v195, v221
	v_cvt_pk_bf16_f32 v224, v218, v219
	v_mul_f32_e32 v222, v92, v220
	v_mul_f32_e32 v223, v93, v221
	v_cvt_pk_bf16_f32 v225, v220, v221
	ds_write_b32 v94, v224 offset:1088
	ds_write_b32 v94, v225 offset:18496
	v_cvt_pk_bf16_f32 v226, v222, v223
	ds_write_b32 v69, v226 offset:36864
	v_lshlrev_b32_e32 v228, 16, v133
	v_and_b32_e32 v229, v71, v133
	v_lshlrev_b32_e32 v230, 16, v105
	v_and_b32_e32 v231, v71, v105
	v_mul_f32_e32 v228, v180, v228
	v_mul_f32_e32 v229, v181, v229
	v_mul_f32_e32 v230, v196, v230
	v_mul_f32_e32 v231, v197, v231
	v_cvt_pk_bf16_f32 v234, v228, v229
	v_mul_f32_e32 v232, v92, v230
	v_mul_f32_e32 v233, v93, v231
	v_cvt_pk_bf16_f32 v235, v230, v231
	ds_write_b32 v94, v234 offset:1360
	ds_write_b32 v94, v235 offset:18768
	v_cvt_pk_bf16_f32 v236, v232, v233
	ds_write_b32 v69, v236 offset:36928
	v_lshlrev_b32_e32 v218, 16, v134
	v_and_b32_e32 v219, v71, v134
	v_lshlrev_b32_e32 v220, 16, v106
	v_and_b32_e32 v221, v71, v106
	v_mul_f32_e32 v218, v182, v218
	v_mul_f32_e32 v219, v183, v219
	v_mul_f32_e32 v220, v198, v220
	v_mul_f32_e32 v221, v199, v221
	v_cvt_pk_bf16_f32 v224, v218, v219
	v_mul_f32_e32 v222, v92, v220
	v_mul_f32_e32 v223, v93, v221
	v_cvt_pk_bf16_f32 v225, v220, v221
	ds_write_b32 v94, v224 offset:1632
	ds_write_b32 v94, v225 offset:19040
	v_cvt_pk_bf16_f32 v226, v222, v223
	ds_write_b32 v69, v226 offset:36992
	v_lshlrev_b32_e32 v228, 16, v135
	v_and_b32_e32 v229, v71, v135
	v_lshlrev_b32_e32 v230, 16, v107
	v_and_b32_e32 v231, v71, v107
	v_mul_f32_e32 v228, v184, v228
	v_mul_f32_e32 v229, v185, v229
	v_mul_f32_e32 v230, v200, v230
	v_mul_f32_e32 v231, v201, v231
	v_cvt_pk_bf16_f32 v234, v228, v229
	v_mul_f32_e32 v232, v92, v230
	v_mul_f32_e32 v233, v93, v231
	v_cvt_pk_bf16_f32 v235, v230, v231
	ds_write_b32 v94, v234 offset:1904
	ds_write_b32 v94, v235 offset:19312
	v_cvt_pk_bf16_f32 v236, v232, v233
	ds_write_b32 v69, v236 offset:37056
	s_waitcnt vmcnt(0)
	s_add_i32 s58, s5, 1
	s_cmp_eq_u32 s50, 3
	s_cbranch_scc1 .LBB0_435
	v_mbcnt_lo_u32_b32 v64, -1, 0
	v_mbcnt_hi_u32_b32 v64, -1, v64
	s_andn2_b64 vcc, exec, s[6:7]
	v_add_u32_e32 v70, s72, v64
	s_mov_b32 s34, s58
	s_cbranch_vccnz .LBB0_426
	s_cmp_gt_u32 s5, 2
	s_mov_b32 s34, s50
	s_cbranch_scc1 .LBB0_426
	s_sub_i32 s34, 2, s5
.LBB0_426:
	s_lshl_b32 s26, s34, 16
	s_lshl_b32 s35, s34, 12
	v_add_u32_e32 v64, s26, v245
	v_add_u32_e32 v65, 0x1000, v64
	s_cmp_lt_i32 s34, 4
	s_cbranch_scc1 .Lscan_pf_noq
	s_bitcmp1_b32 s8, 0
	s_cbranch_scc1 .Lscan_qk_rev0
	global_load_dword v100, v64, s[14:15]
	global_load_dword v128, v64, s[22:23]
	global_load_dword v101, v64, s[14:15] offset:1024
	global_load_dword v129, v64, s[22:23] offset:1024
	global_load_dword v102, v64, s[14:15] offset:2048
	global_load_dword v130, v64, s[22:23] offset:2048
	global_load_dword v103, v64, s[14:15] offset:3072
	global_load_dword v131, v64, s[22:23] offset:3072
	global_load_dword v104, v65, s[14:15]
	global_load_dword v132, v65, s[22:23]
	global_load_dword v105, v65, s[14:15] offset:1024
	global_load_dword v133, v65, s[22:23] offset:1024
	global_load_dword v106, v65, s[14:15] offset:2048
	global_load_dword v134, v65, s[22:23] offset:2048
	global_load_dword v107, v65, s[14:15] offset:3072
	global_load_dword v135, v65, s[22:23] offset:3072
	s_branch .Lscan_qk_done0
.Lscan_qk_rev0:
	global_load_dword v100, v65, s[14:15] offset:3072
	global_load_dword v128, v65, s[22:23] offset:3072
	global_load_dword v101, v65, s[14:15] offset:2048
	global_load_dword v129, v65, s[22:23] offset:2048
	global_load_dword v102, v65, s[14:15] offset:1024
	global_load_dword v130, v65, s[22:23] offset:1024
	global_load_dword v103, v65, s[14:15]
	global_load_dword v131, v65, s[22:23]
	global_load_dword v104, v64, s[14:15] offset:3072
	global_load_dword v132, v64, s[22:23] offset:3072
	global_load_dword v105, v64, s[14:15] offset:2048
	global_load_dword v133, v64, s[22:23] offset:2048
	global_load_dword v106, v64, s[14:15] offset:1024
	global_load_dword v134, v64, s[22:23] offset:1024
	global_load_dword v107, v64, s[14:15]
	global_load_dword v135, v64, s[22:23]

.Lscan_pf_noq:
	s_bitcmp1_b32 s8, 0
	s_cbranch_scc1 .Lscan_qk_rev1
	global_load_dword v100, v64, s[14:15]
	global_load_dword v101, v64, s[14:15] offset:1024
	global_load_dword v102, v64, s[14:15] offset:2048
	global_load_dword v103, v64, s[14:15] offset:3072
	global_load_dword v104, v65, s[14:15]
	global_load_dword v105, v65, s[14:15] offset:1024
	global_load_dword v106, v65, s[14:15] offset:2048
	global_load_dword v107, v65, s[14:15] offset:3072
	s_branch .Lscan_qk_done1

.Lscan_qk_done1:
	v_mov_b32_e32 v128, 0
	v_mov_b32_e32 v129, 0
	v_mov_b32_e32 v130, 0
	v_mov_b32_e32 v131, 0
	v_mov_b32_e32 v132, 0
	v_mov_b32_e32 v133, 0
	v_mov_b32_e32 v134, 0
	v_mov_b32_e32 v135, 0
